# adds: partner-slot loads of the fused-epilogue row-stat exchanges issued together (one round trip instead of three); includes the norm-phase gain-load hoist
# speedup vs baseline: 1.0016x; 1.0007x over previous
; __device__ __forceinline__ float ld_sc1(const float* q) { return __hip_atomic_load(q, __ATOMIC_RELAXED, __HIP_MEMORY_SCOPE_AGENT); }
;   __device__ __forceinline__ void exchange(const f32x4 (&acc)[2][2][4][2], const pg8::Unit& u, int wr, int wc, int fr, int fq, PG8_LAS float* ssq,
;                                            PG8_LAS float* rsv, int tid, float* ex, unsigned* cnt) const {
;     ...
;     if (tid < 256) {
;       const float* e = ex + (size_t)(u.pm * 4) * 256 + tid;
;       const float t = ld_sc1(e) + ld_sc1(e + 256) + ld_sc1(e + 512) + ld_sc1(e + 768);
;       rsv[tid] = rsqrtf(t * (1.f / D) + EPS);
;     }
.LBB0_839:
	s_or_b64 exec, exec, s[0:1]
	s_barrier
	s_and_saveexec_b64 s[0:1], s[4:5]
	s_cbranch_execz .LBB0_841
	s_lshl_b32 s12, s16, 2
	s_ashr_i32 s13, s12, 31
	s_lshl_b64 s[12:13], s[12:13], 10
	s_add_u32 s12, s24, s12
	s_addc_u32 s13, s25, s13
	v_lshl_add_u64 v[128:129], v[154:155], 2, s[12:13]
	global_load_dword v130, v[128:129], off sc1
	global_load_dword v131, v[128:129], off offset:1024 sc1
	global_load_dword v250, v[128:129], off offset:2048 sc1
	global_load_dword v251, v[128:129], off offset:3072 sc1
	s_waitcnt vmcnt(0)
	v_add_f32_e32 v130, v131, v130
	v_add_f32_e32 v130, v130, v250
	v_add_f32_e32 v128, v130, v251
	s_nop 0
	s_nop 0
	v_fmamk_f32 v128, v128, 0x3a800000, v193
	v_cmp_gt_f32_e32 vcc, s92, v128
	v_mul_f32_e32 v129, 0x4b800000, v128
	s_nop 0
	v_cndmask_b32_e32 v128, v128, v129, vcc
	v_rsq_f32_e32 v128, v128
	s_nop 0
	v_mul_f32_e32 v129, 0x45800000, v128
	v_cndmask_b32_e32 v128, v128, v129, vcc
	ds_write_b32 v210, v128 offset:4096

; __device__ __forceinline__ float ld_sc1(const float* q) { return __hip_atomic_load(q, __ATOMIC_RELAXED, __HIP_MEMORY_SCOPE_AGENT); }
;   __device__ __forceinline__ void exchange(const f32x4 (&acc)[2][2][4][2], const pg8::Unit& u, int wr, int wc, int fr, int fq, PG8_LAS float* ssq,
;                                            PG8_LAS float* rsv, int tid, float* ex, unsigned* cnt) const {
;     ...
;     if (tid < 256) {
;       const float* e = ex + (size_t)(u.pm * 4) * 256 + tid;
;       const float t = ld_sc1(e) + ld_sc1(e + 256) + ld_sc1(e + 512) + ld_sc1(e + 768);
;       rsv[tid] = rsqrtf(t * (1.f / D) + EPS);
;     }
.LBB0_870:
	s_or_b64 exec, exec, s[0:1]
	s_barrier
	s_and_saveexec_b64 s[0:1], s[4:5]
	s_cbranch_execz .LBB0_872
	s_lshl_b32 s2, s16, 2
	s_ashr_i32 s3, s2, 31
	s_lshl_b64 s[2:3], s[2:3], 10
	s_add_u32 s2, s20, s2
	s_addc_u32 s3, s21, s3
	v_lshl_add_u64 v[0:1], v[154:155], 2, s[2:3]
	global_load_dword v2, v[0:1], off sc1
	global_load_dword v3, v[0:1], off offset:1024 sc1
	global_load_dword v250, v[0:1], off offset:2048 sc1
	global_load_dword v251, v[0:1], off offset:3072 sc1
	s_waitcnt vmcnt(0)
	v_add_f32_e32 v2, v3, v2
	v_add_f32_e32 v2, v2, v250
	v_add_f32_e32 v0, v2, v251
	s_nop 0
	s_nop 0
	v_fmamk_f32 v0, v0, 0x3a800000, v193
	v_cmp_gt_f32_e32 vcc, s92, v0
	v_mul_f32_e32 v1, 0x4b800000, v0
	s_nop 0
	v_cndmask_b32_e32 v0, v0, v1, vcc
	v_rsq_f32_e32 v0, v0
	s_nop 0
	v_mul_f32_e32 v1, 0x45800000, v0
	v_cndmask_b32_e32 v0, v0, v1, vcc
	ds_write_b32 v210, v0 offset:4096

; __device__ __forceinline__ float ld_sc1(const float* q) { return __hip_atomic_load(q, __ATOMIC_RELAXED, __HIP_MEMORY_SCOPE_AGENT); }
;   __device__ __forceinline__ void exchange(const f32x4 (&acc)[2][2][4][2], const pg8::Unit& u, int wr, int wc, int fr, int fq, PG8_LAS float* ssq,
;                                            PG8_LAS float* rsv, int tid, float* ex, unsigned* cnt) const {
;     ...
;     if (tid < 256) {
;       const float* e = ex + (size_t)(u.pm * 4) * 256 + tid;
;       const float t = ld_sc1(e) + ld_sc1(e + 256) + ld_sc1(e + 512) + ld_sc1(e + 768);
;       rsv[tid] = rsqrtf(t * (1.f / D) + EPS);
;     }
.LBB0_1110:
	s_or_b64 exec, exec, s[0:1]
	s_mov_b64 s[18:19], s[56:57]
	s_barrier
	s_and_saveexec_b64 s[0:1], s[6:7]
	s_cbranch_execz .LBB0_1112
	s_lshl_b32 s12, s16, 2
	s_ashr_i32 s13, s12, 31
	s_lshl_b64 s[12:13], s[12:13], 10
	s_add_u32 s12, s24, s12
	s_addc_u32 s13, s25, s13
	v_lshl_add_u64 v[128:129], v[154:155], 2, s[12:13]
	global_load_dword v130, v[128:129], off sc1
	global_load_dword v131, v[128:129], off offset:1024 sc1
	global_load_dword v250, v[128:129], off offset:2048 sc1
	global_load_dword v251, v[128:129], off offset:3072 sc1
	s_waitcnt vmcnt(0)
	v_add_f32_e32 v130, v131, v130
	v_add_f32_e32 v130, v130, v250
	v_add_f32_e32 v128, v130, v251
	s_nop 0
	s_nop 0
	v_fmamk_f32 v128, v128, 0x3a800000, v193
	v_cmp_gt_f32_e32 vcc, s92, v128
	v_mul_f32_e32 v129, 0x4b800000, v128
	s_nop 0
	v_cndmask_b32_e32 v128, v128, v129, vcc
	v_rsq_f32_e32 v128, v128
	s_nop 0
	v_mul_f32_e32 v129, 0x45800000, v128
	v_cndmask_b32_e32 v128, v128, v129, vcc
	ds_write_b32 v210, v128 offset:4096

; __device__ __forceinline__ float ld_sc1(const float* q) { return __hip_atomic_load(q, __ATOMIC_RELAXED, __HIP_MEMORY_SCOPE_AGENT); }
;   __device__ __forceinline__ void exchange(const f32x4 (&acc)[2][2][4][2], const pg8::Unit& u, int wr, int wc, int fr, int fq, PG8_LAS float* ssq,
;                                            PG8_LAS float* rsv, int tid, float* ex, unsigned* cnt) const {
;     ...
;     if (tid < 256) {
;       const float* e = ex + (size_t)(u.pm * 4) * 256 + tid;
;       const float t = ld_sc1(e) + ld_sc1(e + 256) + ld_sc1(e + 512) + ld_sc1(e + 768);
;       rsv[tid] = rsqrtf(t * (1.f / D) + EPS);
;     }
.LBB0_1141:
	s_or_b64 exec, exec, s[0:1]
	s_barrier
	s_and_saveexec_b64 s[0:1], s[6:7]
	s_cbranch_execz .LBB0_1143
	s_lshl_b32 s4, s16, 2
	s_ashr_i32 s5, s4, 31
	s_lshl_b64 s[4:5], s[4:5], 10
	s_add_u32 s4, s20, s4
	s_addc_u32 s5, s21, s5
	v_lshl_add_u64 v[0:1], v[154:155], 2, s[4:5]
	global_load_dword v2, v[0:1], off sc1
	global_load_dword v3, v[0:1], off offset:1024 sc1
	global_load_dword v250, v[0:1], off offset:2048 sc1
	global_load_dword v251, v[0:1], off offset:3072 sc1
	s_waitcnt vmcnt(0)
	v_add_f32_e32 v2, v3, v2
	v_add_f32_e32 v2, v2, v250
	v_add_f32_e32 v0, v2, v251
	s_nop 0
	s_nop 0
	v_fmamk_f32 v0, v0, 0x3a800000, v193
	v_cmp_gt_f32_e32 vcc, s92, v0
	v_mul_f32_e32 v1, 0x4b800000, v0
	s_nop 0
	v_cndmask_b32_e32 v0, v0, v1, vcc
	v_rsq_f32_e32 v0, v0
	s_nop 0
	v_mul_f32_e32 v1, 0x45800000, v0
	v_cndmask_b32_e32 v0, v0, v1, vcc
	ds_write_b32 v210, v0 offset:4096

; __device__ __forceinline__ float ld_sc1(const float* q) { return __hip_atomic_load(q, __ATOMIC_RELAXED, __HIP_MEMORY_SCOPE_AGENT); }
;   __device__ __forceinline__ void exchange(const f32x4 (&acc)[2][2][4][2], const pg8::Unit& u, int wr, int wc, int fr, int fq, PG8_LAS float* ssq,
;                                            PG8_LAS float* rsv, int tid, float* ex, unsigned* cnt) const {
;     ...
;     if (tid < 256) {
;       const float* e = ex + (size_t)(u.pm * 4) * 256 + tid;
;       const float t = ld_sc1(e) + ld_sc1(e + 256) + ld_sc1(e + 512) + ld_sc1(e + 768);
;       rsv[tid] = rsqrtf(t * (1.f / D) + EPS);
;     }
.LBB0_1201:
	s_or_b64 exec, exec, s[4:5]
	s_mov_b64 s[6:7], s[56:57]
	s_barrier
	s_and_saveexec_b64 s[4:5], s[0:1]
	s_cbranch_execz .LBB0_1203
	s_lshl_b32 s0, s8, 2
	s_ashr_i32 s1, s0, 31
	s_lshl_b64 s[0:1], s[0:1], 10
	s_add_u32 s0, s20, s0
	s_addc_u32 s1, s21, s1
	v_lshl_add_u64 v[128:129], v[128:129], 2, s[0:1]
	global_load_dword v131, v[128:129], off sc1
	global_load_dword v132, v[128:129], off offset:1024 sc1
	global_load_dword v250, v[128:129], off offset:2048 sc1
	global_load_dword v251, v[128:129], off offset:3072 sc1
	s_waitcnt vmcnt(0)
	v_add_f32_e32 v131, v132, v131
	v_add_f32_e32 v131, v131, v250
	v_add_f32_e32 v128, v131, v251
	s_nop 0
	s_nop 0
	v_fmamk_f32 v128, v128, 0x3a800000, v193
	v_cmp_gt_f32_e32 vcc, s92, v128
	v_mul_f32_e32 v129, 0x4b800000, v128
	s_nop 0
	v_cndmask_b32_e32 v128, v128, v129, vcc
	v_rsq_f32_e32 v128, v128
	s_nop 0
	v_mul_f32_e32 v129, 0x45800000, v128
	v_cndmask_b32_e32 v128, v128, v129, vcc
	ds_write_b32 v130, v128 offset:4096
